# v56 + P1 sigmoid epilogue: v_mov+v_fmac fused into one v_fma_f32 (instruction selection)
# speedup vs baseline: 1.0093x; 1.0037x over previous
; #define GAS1 __attribute__((address_space(1)))
;     __device__ __forceinline__ void operator()(const f32x4 (&acc)[2][2][4][2], const Unit& u, int wr, int wc, int fr, int fq) const {
;     ...
;                 f32x4 v0 = acc[ai][bj][m][0], v1 = acc[ai][bj][m][1];
;                 if (MODE == 1) {
;                     if (special) {
;                         const f32x4 b0 = *(const GAS1 f32x4*)(bias + col) * -1.4426950408889634f, b1 = *(const GAS1 f32x4*)(bias + col + 4) * -1.4426950408889634f;
; #pragma unroll
;                         for (int j = 0; j < 4; ++j) { v0[j] = __builtin_amdgcn_rcpf(1.0f + __builtin_amdgcn_exp2f(__builtin_fmaf(v0[j], -1.4426950408889634f, b0[j])));
;                                                       v1[j] = __builtin_amdgcn_rcpf(1.0f + __builtin_amdgcn_exp2f(__builtin_fmaf(v1[j], -1.4426950408889634f, b1[j]))); }
;                     }
;                 }
;                 if (MODE == 2) {
;                     if (special) {
;                         const int fi = ((col & 63) >> 3) * 4;
;                         const f32x4 c = *(const GAS1 f32x4*)(cosT + (size_t)row * 32 + fi), s_ = *(const GAS1 f32x4*)(sinT + (size_t)row * 32 + fi);
;                         const f32x4 o1 = v0 * c - v1 * s_, o2 = v1 * c + v0 * s_; v0 = o1; v1 = o2;
;                     }
;                 }
;                 if (MODE == 3 || MODE == 4) {
;                     const u32x4 gw = *(const GAS1 u32x4*)(G + (size_t)row * ldg + col);
;                     const f32x4 g0 = {bf_lo(gw.x), bf_hi(gw.x), bf_lo(gw.y), bf_hi(gw.y)}, g1 = {bf_lo(gw.z), bf_hi(gw.z), bf_lo(gw.w), bf_hi(gw.w)};
;                     v0 = v0 * g0; v1 = v1 * g1;
;                     if (MODE == 4) {
;                         const u32x4 ow = *(const GAS1 u32x4*)((const bf16_t*)O + (size_t)row * ldc + col);
;                         const f32x4 o0 = {bf_lo(ow.x), bf_hi(ow.x), bf_lo(ow.y), bf_hi(ow.y)}, o1 = {bf_lo(ow.z), bf_hi(ow.z), bf_lo(ow.w), bf_hi(ow.w)};
;                         v0 += o0; v1 += o1;
;                     }
;                 }
;                 u32x4 w; w.x = cvt_pk_bf16(v0[0], v0[1]); w.y = cvt_pk_bf16(v0[2], v0[3]); w.z = cvt_pk_bf16(v1[0], v1[1]); w.w = cvt_pk_bf16(v1[2], v1[3]);
;                 if (bj == 0) asm volatile("ds_write_b128 %0, %1" :: "v"(wa), "v"(w)); else asm volatile("ds_write_b128 %0, %1 offset:64" :: "v"(wa), "v"(w));
;             }
.LBB0_767:
	s_mov_b32 s99, 0xbfb8aa3b
	s_lshl_b32 s38, s6, 8
	s_cmp_lt_i32 s6, 16
	v_or_b32_e32 v146, s38, v152
	s_cselect_b64 s[42:43], -1, 0
	s_cmp_gt_i32 s6, 15
	v_ashrrev_i32_e32 v147, 31, v146
	s_cbranch_scc1 .LBB0_769
	v_lshl_add_u64 v[162:163], v[146:147], 2, s[10:11]
	global_load_dwordx4 v[192:195], v[162:163], off offset:128
	global_load_dwordx4 v[196:199], v[162:163], off offset:144
	global_load_dwordx4 v[158:161], v[162:163], off
	s_nop 0
	global_load_dwordx4 v[162:165], v[162:163], off offset:16
	s_waitcnt vmcnt(0)
	v_mul_f32_e32 v158, 0xbfb8aa3b, v158
	v_mul_f32_e32 v162, 0xbfb8aa3b, v162
	v_mul_f32_e32 v159, 0xbfb8aa3b, v159
	v_mul_f32_e32 v163, 0xbfb8aa3b, v163
	v_mul_f32_e32 v160, 0xbfb8aa3b, v160
	v_mul_f32_e32 v164, 0xbfb8aa3b, v164
	v_mul_f32_e32 v161, 0xbfb8aa3b, v161
	v_mul_f32_e32 v165, 0xbfb8aa3b, v165
	v_mov_b32_e32 v176, v158
	v_mov_b32_e32 v177, v159
	v_mov_b32_e32 v178, v160
	v_mov_b32_e32 v179, v161
	v_mov_b32_e32 v180, v162
	v_mov_b32_e32 v181, v163
	v_mov_b32_e32 v182, v164
	v_mov_b32_e32 v183, v165
	v_mul_f32_e32 v184, 0xbfb8aa3b, v192
	v_mul_f32_e32 v185, 0xbfb8aa3b, v193
	v_mul_f32_e32 v186, 0xbfb8aa3b, v194
	v_mul_f32_e32 v187, 0xbfb8aa3b, v195
	v_mul_f32_e32 v188, 0xbfb8aa3b, v196
	v_mul_f32_e32 v189, 0xbfb8aa3b, v197
	v_mul_f32_e32 v190, 0xbfb8aa3b, v198
	v_mul_f32_e32 v191, 0xbfb8aa3b, v199
	v_fmac_f32_e32 v158, 0xbfb8aa3b, v124
	v_fmac_f32_e32 v162, 0xbfb8aa3b, v120
	v_fmac_f32_e32 v159, 0xbfb8aa3b, v125
	v_fmac_f32_e32 v163, 0xbfb8aa3b, v121
	v_fmac_f32_e32 v160, 0xbfb8aa3b, v126
	v_fmac_f32_e32 v164, 0xbfb8aa3b, v122
	v_fmac_f32_e32 v161, 0xbfb8aa3b, v127
	v_fmac_f32_e32 v165, 0xbfb8aa3b, v123
	v_exp_f32_e32 v120, v158
	v_exp_f32_e32 v121, v162
	v_exp_f32_e32 v122, v159
	v_exp_f32_e32 v123, v163
	v_exp_f32_e32 v124, v160
	v_exp_f32_e32 v125, v164
	v_exp_f32_e32 v126, v161
	v_exp_f32_e32 v127, v165
	v_add_f32_e32 v120, 1.0, v120
	v_add_f32_e32 v121, 1.0, v121
	v_add_f32_e32 v122, 1.0, v122
	v_add_f32_e32 v123, 1.0, v123
	v_add_f32_e32 v158, 1.0, v124
	v_add_f32_e32 v159, 1.0, v125
	v_add_f32_e32 v160, 1.0, v126
	v_add_f32_e32 v161, 1.0, v127
	v_rcp_f32_e32 v124, v120
	v_rcp_f32_e32 v120, v121
	v_rcp_f32_e32 v125, v122
	v_rcp_f32_e32 v121, v123
	v_rcp_f32_e32 v126, v158
	v_rcp_f32_e32 v122, v159
	v_rcp_f32_e32 v127, v160
	v_rcp_f32_e32 v123, v161
.LBB0_769:
	v_cvt_pk_bf16_f32 v124, v124, v125
	v_cvt_pk_bf16_f32 v125, v126, v127
	v_cvt_pk_bf16_f32 v126, v120, v121
	v_cndmask_b32_e64 v120, 0, 1, s[42:43]
	v_cmp_ne_u32_e64 s[6:7], 1, v120
	s_andn2_b64 vcc, exec, s[42:43]
	v_cvt_pk_bf16_f32 v127, v122, v123
	s_nop 0
	ds_write_b128 v153, v[124:127]
	s_cbranch_vccnz .LBB0_771
	v_fma_f32 v120, v116, s99, v184
	v_fma_f32 v124, v112, s99, v188
	v_fma_f32 v121, v117, s99, v185
	v_fma_f32 v125, v113, s99, v189
	v_fma_f32 v122, v118, s99, v186
	v_fma_f32 v126, v114, s99, v190
	v_fma_f32 v123, v119, s99, v187
	v_fma_f32 v127, v115, s99, v191
	v_exp_f32_e32 v112, v120
	v_exp_f32_e32 v113, v124
	v_exp_f32_e32 v114, v121
	v_exp_f32_e32 v115, v125
	v_exp_f32_e32 v116, v122
	v_exp_f32_e32 v117, v126
	v_exp_f32_e32 v118, v123
	v_exp_f32_e32 v119, v127
	v_add_f32_e32 v112, 1.0, v112
	v_add_f32_e32 v113, 1.0, v113
	v_add_f32_e32 v114, 1.0, v114
	v_add_f32_e32 v115, 1.0, v115
	v_add_f32_e32 v120, 1.0, v116
	v_add_f32_e32 v121, 1.0, v117
	v_add_f32_e32 v122, 1.0, v118
	v_add_f32_e32 v123, 1.0, v119
	v_rcp_f32_e32 v116, v112
	v_rcp_f32_e32 v112, v113
	v_rcp_f32_e32 v117, v114
	v_rcp_f32_e32 v113, v115
	v_rcp_f32_e32 v118, v120
	v_rcp_f32_e32 v114, v121
	v_rcp_f32_e32 v119, v122
	v_rcp_f32_e32 v115, v123
.LBB0_771:
	v_cvt_pk_bf16_f32 v116, v116, v117
	v_cvt_pk_bf16_f32 v117, v118, v119
	v_cvt_pk_bf16_f32 v118, v112, v113
	v_cvt_pk_bf16_f32 v119, v114, v115
	s_and_b64 vcc, exec, s[6:7]
	ds_write_b128 v153, v[116:119] offset:64
	ds_read_b128 v[116:119], v154
	ds_read_b128 v[112:115], v154 offset:1152
	s_cbranch_vccnz .LBB0_773
	v_fma_f32 v120, v108, s99, v176
	v_fma_f32 v124, v104, s99, v180
	v_fma_f32 v121, v109, s99, v177
	v_fma_f32 v125, v105, s99, v181
	v_fma_f32 v122, v110, s99, v178
	v_fma_f32 v126, v106, s99, v182
	v_fma_f32 v123, v111, s99, v179
	v_fma_f32 v127, v107, s99, v183
	v_exp_f32_e32 v104, v120
	v_exp_f32_e32 v105, v124
	v_exp_f32_e32 v106, v121
	v_exp_f32_e32 v107, v125
	v_exp_f32_e32 v108, v122
	v_exp_f32_e32 v109, v126
	v_exp_f32_e32 v110, v123
	v_exp_f32_e32 v111, v127
	v_add_f32_e32 v104, 1.0, v104
	v_add_f32_e32 v105, 1.0, v105
	v_add_f32_e32 v106, 1.0, v106
	v_add_f32_e32 v107, 1.0, v107
	v_add_f32_e32 v120, 1.0, v108
	v_add_f32_e32 v121, 1.0, v109
	v_add_f32_e32 v122, 1.0, v110
	v_add_f32_e32 v123, 1.0, v111
	v_rcp_f32_e32 v108, v104
	v_rcp_f32_e32 v104, v105
	v_rcp_f32_e32 v109, v106
	v_rcp_f32_e32 v105, v107
	v_rcp_f32_e32 v110, v120
	v_rcp_f32_e32 v106, v121
	v_rcp_f32_e32 v111, v122
	v_rcp_f32_e32 v107, v123
.LBB0_773:
	s_and_b64 vcc, exec, s[6:7]
	v_cvt_pk_bf16_f32 v108, v108, v109
	v_cvt_pk_bf16_f32 v109, v110, v111
	v_cvt_pk_bf16_f32 v110, v104, v105
	v_cvt_pk_bf16_f32 v111, v106, v107
	s_nop 0
	ds_write_b128 v153, v[108:111]
	s_cbranch_vccnz .LBB0_775
	v_fma_f32 v104, v100, s99, v184
	v_fma_f32 v108, v96, s99, v188
	v_fma_f32 v105, v101, s99, v185
	v_fma_f32 v109, v97, s99, v189
	v_fma_f32 v106, v102, s99, v186
	v_fma_f32 v110, v98, s99, v190
	v_fma_f32 v107, v103, s99, v187
	v_fma_f32 v111, v99, s99, v191
	v_exp_f32_e32 v96, v104
	v_exp_f32_e32 v97, v108
	v_exp_f32_e32 v98, v105
	v_exp_f32_e32 v99, v109
	v_exp_f32_e32 v100, v106
	v_exp_f32_e32 v101, v110
	v_exp_f32_e32 v102, v107
	v_exp_f32_e32 v103, v111
	v_add_f32_e32 v96, 1.0, v96
	v_add_f32_e32 v97, 1.0, v97
	v_add_f32_e32 v98, 1.0, v98
	v_add_f32_e32 v99, 1.0, v99
	v_add_f32_e32 v104, 1.0, v100
	v_add_f32_e32 v105, 1.0, v101
	v_add_f32_e32 v106, 1.0, v102
	v_add_f32_e32 v107, 1.0, v103
	v_rcp_f32_e32 v100, v96
	v_rcp_f32_e32 v96, v97
	v_rcp_f32_e32 v101, v98
	v_rcp_f32_e32 v97, v99
	v_rcp_f32_e32 v102, v104
	v_rcp_f32_e32 v98, v105
	v_rcp_f32_e32 v103, v106
	v_rcp_f32_e32 v99, v107
; #define GAS1 __attribute__((address_space(1)))
;     __device__ __forceinline__ void operator()(const f32x4 (&acc)[2][2][4][2], const Unit& u, int wr, int wc, int fr, int fq) const {
;     ...
;                 f32x4 v0 = acc[ai][bj][m][0], v1 = acc[ai][bj][m][1];
;                 if (MODE == 1) {
;                     if (special) {
;                         const f32x4 b0 = *(const GAS1 f32x4*)(bias + col) * -1.4426950408889634f, b1 = *(const GAS1 f32x4*)(bias + col + 4) * -1.4426950408889634f;
; #pragma unroll
;                         for (int j = 0; j < 4; ++j) { v0[j] = __builtin_amdgcn_rcpf(1.0f + __builtin_amdgcn_exp2f(__builtin_fmaf(v0[j], -1.4426950408889634f, b0[j])));
;                                                       v1[j] = __builtin_amdgcn_rcpf(1.0f + __builtin_amdgcn_exp2f(__builtin_fmaf(v1[j], -1.4426950408889634f, b1[j]))); }
;                     }
;                 }
;                 if (MODE == 2) {
;                     if (special) {
;                         const int fi = ((col & 63) >> 3) * 4;
;                         const f32x4 c = *(const GAS1 f32x4*)(cosT + (size_t)row * 32 + fi), s_ = *(const GAS1 f32x4*)(sinT + (size_t)row * 32 + fi);
;                         const f32x4 o1 = v0 * c - v1 * s_, o2 = v1 * c + v0 * s_; v0 = o1; v1 = o2;
;                     }
;                 }
;                 if (MODE == 3 || MODE == 4) {
;                     const u32x4 gw = *(const GAS1 u32x4*)(G + (size_t)row * ldg + col);
;                     const f32x4 g0 = {bf_lo(gw.x), bf_hi(gw.x), bf_lo(gw.y), bf_hi(gw.y)}, g1 = {bf_lo(gw.z), bf_hi(gw.z), bf_lo(gw.w), bf_hi(gw.w)};
;                     v0 = v0 * g0; v1 = v1 * g1;
;                     if (MODE == 4) {
;                         const u32x4 ow = *(const GAS1 u32x4*)((const bf16_t*)O + (size_t)row * ldc + col);
;                         const f32x4 o0 = {bf_lo(ow.x), bf_hi(ow.x), bf_lo(ow.y), bf_hi(ow.y)}, o1 = {bf_lo(ow.z), bf_hi(ow.z), bf_lo(ow.w), bf_hi(ow.w)};
;                         v0 += o0; v1 += o1;
;                     }
;                 }
;                 u32x4 w; w.x = cvt_pk_bf16(v0[0], v0[1]); w.y = cvt_pk_bf16(v0[2], v0[3]); w.z = cvt_pk_bf16(v1[0], v1[1]); w.w = cvt_pk_bf16(v1[2], v1[3]);
;                 if (bj == 0) asm volatile("ds_write_b128 %0, %1" :: "v"(wa), "v"(w)); else asm volatile("ds_write_b128 %0, %1 offset:64" :: "v"(wa), "v"(w));
;             }
.LBB0_775:
	v_lshl_add_u32 v106, s36, 8, v151
	v_mov_b64_e32 v[104:105], s[16:17]
	v_mad_i64_i32 v[104:105], s[40:41], v106, s71, v[104:105]
	s_ashr_i32 s39, s38, 31
	v_lshl_add_u64 v[104:105], s[38:39], 1, v[104:105]
	v_lshl_add_u64 v[104:105], v[104:105], 0, s[12:13]
	v_lshl_add_u64 v[104:105], v[104:105], 0, v[136:137]
	v_add_co_u32_e32 v106, vcc, 0x1c000, v104
	v_cvt_pk_bf16_f32 v100, v100, v101
	v_cvt_pk_bf16_f32 v101, v102, v103
	v_cvt_pk_bf16_f32 v102, v96, v97
	v_cvt_pk_bf16_f32 v103, v98, v99
	s_nop 1
	v_addc_co_u32_e32 v107, vcc, 0, v105, vcc
	s_and_b64 vcc, exec, s[6:7]
	ds_write_b128 v153, v[100:103] offset:64
	ds_read_b128 v[100:103], v154
	ds_read_b128 v[96:99], v154 offset:1152
	s_waitcnt lgkmcnt(4)
	global_store_dwordx4 v[104:105], v[116:119], off nt
	global_store_dwordx4 v[106:107], v[112:115], off nt
	s_cbranch_vccnz .LBB0_777
	v_fma_f32 v106, v92, s99, v176
	v_fma_f32 v110, v88, s99, v180
	v_fma_f32 v107, v93, s99, v177
	v_fma_f32 v111, v89, s99, v181
	v_fma_f32 v108, v94, s99, v178
	v_fma_f32 v112, v90, s99, v182
	v_fma_f32 v109, v95, s99, v179
	v_fma_f32 v113, v91, s99, v183
	v_exp_f32_e32 v88, v106
	v_exp_f32_e32 v89, v110
	v_exp_f32_e32 v90, v107
	v_exp_f32_e32 v91, v111
	v_exp_f32_e32 v92, v108
	v_exp_f32_e32 v93, v112
	v_exp_f32_e32 v94, v109
	v_exp_f32_e32 v95, v113
	v_add_f32_e32 v88, 1.0, v88
	v_add_f32_e32 v89, 1.0, v89
	v_add_f32_e32 v90, 1.0, v90
	v_add_f32_e32 v91, 1.0, v91
	v_add_f32_e32 v106, 1.0, v92
	v_add_f32_e32 v107, 1.0, v93
	v_add_f32_e32 v108, 1.0, v94
	v_add_f32_e32 v109, 1.0, v95
	v_rcp_f32_e32 v92, v88
	v_rcp_f32_e32 v88, v89
	v_rcp_f32_e32 v93, v90
	v_rcp_f32_e32 v89, v91
	v_rcp_f32_e32 v94, v106
	v_rcp_f32_e32 v90, v107
	v_rcp_f32_e32 v95, v108
	v_rcp_f32_e32 v91, v109
.LBB0_777:
	s_and_b64 vcc, exec, s[6:7]
	v_cvt_pk_bf16_f32 v92, v92, v93
	v_cvt_pk_bf16_f32 v93, v94, v95
	v_cvt_pk_bf16_f32 v94, v88, v89
	v_cvt_pk_bf16_f32 v95, v90, v91
	s_nop 0
	ds_write_b128 v153, v[92:95]
	s_cbranch_vccnz .LBB0_779
	v_fma_f32 v88, v84, s99, v184
	v_fma_f32 v92, v80, s99, v188
	v_fma_f32 v89, v85, s99, v185
	v_fma_f32 v93, v81, s99, v189
	v_fma_f32 v90, v86, s99, v186
	v_fma_f32 v94, v82, s99, v190
	v_fma_f32 v91, v87, s99, v187
	v_fma_f32 v95, v83, s99, v191
	v_exp_f32_e32 v80, v88
	v_exp_f32_e32 v81, v92
	v_exp_f32_e32 v82, v89
	v_exp_f32_e32 v83, v93
	v_exp_f32_e32 v84, v90
	v_exp_f32_e32 v85, v94
	v_exp_f32_e32 v86, v91
	v_exp_f32_e32 v87, v95
	v_add_f32_e32 v80, 1.0, v80
	v_add_f32_e32 v81, 1.0, v81
	v_add_f32_e32 v82, 1.0, v82
	v_add_f32_e32 v83, 1.0, v83
	v_add_f32_e32 v88, 1.0, v84
	v_add_f32_e32 v89, 1.0, v85
	v_add_f32_e32 v90, 1.0, v86
	v_add_f32_e32 v91, 1.0, v87
	v_rcp_f32_e32 v84, v80
	v_rcp_f32_e32 v80, v81
	v_rcp_f32_e32 v85, v82
	v_rcp_f32_e32 v81, v83
	v_rcp_f32_e32 v86, v88
	v_rcp_f32_e32 v82, v89
	v_rcp_f32_e32 v87, v90
	v_rcp_f32_e32 v83, v91
.LBB0_779:
	v_add_co_u32_e32 v88, vcc, 0x38000, v104
	v_cvt_pk_bf16_f32 v84, v84, v85
	v_cvt_pk_bf16_f32 v85, v86, v87
	v_cvt_pk_bf16_f32 v86, v80, v81
	v_cvt_pk_bf16_f32 v87, v82, v83
	s_nop 1
	v_addc_co_u32_e32 v89, vcc, 0, v105, vcc
	ds_write_b128 v153, v[84:87] offset:64
	ds_read_b128 v[84:87], v154
	ds_read_b128 v[80:83], v154 offset:1152
	s_waitcnt lgkmcnt(4)
	global_store_dwordx4 v[88:89], v[100:103], off nt
	v_add_co_u32_e32 v88, vcc, 0x54000, v104
	s_nop 1
	v_addc_co_u32_e32 v89, vcc, 0, v105, vcc
	s_and_b64 vcc, exec, s[6:7]
	global_store_dwordx4 v[88:89], v[96:99], off nt
	s_cbranch_vccnz .LBB0_781
	v_fma_f32 v88, v76, s99, v176
	v_fma_f32 v92, v72, s99, v180
	v_fma_f32 v89, v77, s99, v177
	v_fma_f32 v93, v73, s99, v181
	v_fma_f32 v90, v78, s99, v178
	v_fma_f32 v94, v74, s99, v182
	v_fma_f32 v91, v79, s99, v179
	v_fma_f32 v95, v75, s99, v183
	v_exp_f32_e32 v72, v88
	v_exp_f32_e32 v73, v92
	v_exp_f32_e32 v74, v89
	v_exp_f32_e32 v75, v93
	v_exp_f32_e32 v76, v90
	v_exp_f32_e32 v77, v94
	v_exp_f32_e32 v78, v91
	v_exp_f32_e32 v79, v95
	v_add_f32_e32 v72, 1.0, v72
	v_add_f32_e32 v73, 1.0, v73
	v_add_f32_e32 v74, 1.0, v74
	v_add_f32_e32 v75, 1.0, v75
	v_add_f32_e32 v88, 1.0, v76
	v_add_f32_e32 v89, 1.0, v77
	v_add_f32_e32 v90, 1.0, v78
	v_add_f32_e32 v91, 1.0, v79
	v_rcp_f32_e32 v76, v72
	v_rcp_f32_e32 v72, v73
	v_rcp_f32_e32 v77, v74
	v_rcp_f32_e32 v73, v75
	v_rcp_f32_e32 v78, v88
	v_rcp_f32_e32 v74, v89
	v_rcp_f32_e32 v79, v90
	v_rcp_f32_e32 v75, v91
.LBB0_781:
	s_and_b64 vcc, exec, s[6:7]
	v_cvt_pk_bf16_f32 v76, v76, v77
	v_cvt_pk_bf16_f32 v77, v78, v79
	v_cvt_pk_bf16_f32 v78, v72, v73
	v_cvt_pk_bf16_f32 v79, v74, v75
	s_nop 0
	ds_write_b128 v153, v[76:79]
	s_cbranch_vccnz .LBB0_783
	v_fma_f32 v72, v68, s99, v184
	v_fma_f32 v76, v64, s99, v188
	v_fma_f32 v73, v69, s99, v185
	v_fma_f32 v77, v65, s99, v189
	v_fma_f32 v74, v70, s99, v186
	v_fma_f32 v78, v66, s99, v190
	v_fma_f32 v75, v71, s99, v187
	v_fma_f32 v79, v67, s99, v191
	v_exp_f32_e32 v64, v72
	v_exp_f32_e32 v65, v76
	v_exp_f32_e32 v66, v73
	v_exp_f32_e32 v67, v77
	v_exp_f32_e32 v68, v74
	v_exp_f32_e32 v69, v78
	v_exp_f32_e32 v70, v75
	v_exp_f32_e32 v71, v79
	v_add_f32_e32 v64, 1.0, v64
	v_add_f32_e32 v65, 1.0, v65
	v_add_f32_e32 v66, 1.0, v66
	v_add_f32_e32 v67, 1.0, v67
	v_add_f32_e32 v72, 1.0, v68
	v_add_f32_e32 v73, 1.0, v69
	v_add_f32_e32 v74, 1.0, v70
	v_add_f32_e32 v75, 1.0, v71
	v_rcp_f32_e32 v68, v64
	v_rcp_f32_e32 v64, v65
	v_rcp_f32_e32 v69, v66
	v_rcp_f32_e32 v65, v67
	v_rcp_f32_e32 v70, v72
	v_rcp_f32_e32 v66, v73
	v_rcp_f32_e32 v71, v74
	v_rcp_f32_e32 v67, v75
; #define GAS1 __attribute__((address_space(1)))
;     __device__ __forceinline__ void operator()(const f32x4 (&acc)[2][2][4][2], const Unit& u, int wr, int wc, int fr, int fq) const {
;     ...
;                 f32x4 v0 = acc[ai][bj][m][0], v1 = acc[ai][bj][m][1];
;                 if (MODE == 1) {
;                     if (special) {
;                         const f32x4 b0 = *(const GAS1 f32x4*)(bias + col) * -1.4426950408889634f, b1 = *(const GAS1 f32x4*)(bias + col + 4) * -1.4426950408889634f;
; #pragma unroll
;                         for (int j = 0; j < 4; ++j) { v0[j] = __builtin_amdgcn_rcpf(1.0f + __builtin_amdgcn_exp2f(__builtin_fmaf(v0[j], -1.4426950408889634f, b0[j])));
;                                                       v1[j] = __builtin_amdgcn_rcpf(1.0f + __builtin_amdgcn_exp2f(__builtin_fmaf(v1[j], -1.4426950408889634f, b1[j]))); }
;                     }
;                 }
;                 if (MODE == 2) {
;                     if (special) {
;                         const int fi = ((col & 63) >> 3) * 4;
;                         const f32x4 c = *(const GAS1 f32x4*)(cosT + (size_t)row * 32 + fi), s_ = *(const GAS1 f32x4*)(sinT + (size_t)row * 32 + fi);
;                         const f32x4 o1 = v0 * c - v1 * s_, o2 = v1 * c + v0 * s_; v0 = o1; v1 = o2;
;                     }
;                 }
;                 if (MODE == 3 || MODE == 4) {
;                     const u32x4 gw = *(const GAS1 u32x4*)(G + (size_t)row * ldg + col);
;                     const f32x4 g0 = {bf_lo(gw.x), bf_hi(gw.x), bf_lo(gw.y), bf_hi(gw.y)}, g1 = {bf_lo(gw.z), bf_hi(gw.z), bf_lo(gw.w), bf_hi(gw.w)};
;                     v0 = v0 * g0; v1 = v1 * g1;
;                     if (MODE == 4) {
;                         const u32x4 ow = *(const GAS1 u32x4*)((const bf16_t*)O + (size_t)row * ldc + col);
;                         const f32x4 o0 = {bf_lo(ow.x), bf_hi(ow.x), bf_lo(ow.y), bf_hi(ow.y)}, o1 = {bf_lo(ow.z), bf_hi(ow.z), bf_lo(ow.w), bf_hi(ow.w)};
;                         v0 += o0; v1 += o1;
;                     }
;                 }
;                 u32x4 w; w.x = cvt_pk_bf16(v0[0], v0[1]); w.y = cvt_pk_bf16(v0[2], v0[3]); w.z = cvt_pk_bf16(v1[0], v1[1]); w.w = cvt_pk_bf16(v1[2], v1[3]);
;                 if (bj == 0) asm volatile("ds_write_b128 %0, %1" :: "v"(wa), "v"(w)); else asm volatile("ds_write_b128 %0, %1 offset:64" :: "v"(wa), "v"(w));
;             }
.LBB0_783:
	v_add_co_u32_e32 v72, vcc, 0x70000, v104
	v_cvt_pk_bf16_f32 v68, v68, v69
	v_cvt_pk_bf16_f32 v69, v70, v71
	v_cvt_pk_bf16_f32 v70, v64, v65
	v_cvt_pk_bf16_f32 v71, v66, v67
	s_nop 1
	v_addc_co_u32_e32 v73, vcc, 0, v105, vcc
	ds_write_b128 v153, v[68:71] offset:64
	ds_read_b128 v[68:71], v154
	ds_read_b128 v[64:67], v154 offset:1152
	s_waitcnt lgkmcnt(4)
	global_store_dwordx4 v[72:73], v[84:87], off nt
	v_add_co_u32_e32 v72, vcc, 0x8c000, v104
	s_nop 1
	v_addc_co_u32_e32 v73, vcc, 0, v105, vcc
	s_and_b64 vcc, exec, s[6:7]
	global_store_dwordx4 v[72:73], v[80:83], off nt
	s_cbranch_vccnz .LBB0_785
	v_fma_f32 v72, v60, s99, v176
	v_fma_f32 v76, v56, s99, v180
	v_fma_f32 v73, v61, s99, v177
	v_fma_f32 v77, v57, s99, v181
	v_fma_f32 v74, v62, s99, v178
	v_fma_f32 v78, v58, s99, v182
	v_fma_f32 v75, v63, s99, v179
	v_fma_f32 v79, v59, s99, v183
	v_exp_f32_e32 v56, v72
	v_exp_f32_e32 v57, v76
	v_exp_f32_e32 v58, v73
	v_exp_f32_e32 v59, v77
	v_exp_f32_e32 v60, v74
	v_exp_f32_e32 v61, v78
	v_exp_f32_e32 v62, v75
	v_exp_f32_e32 v63, v79
	v_add_f32_e32 v56, 1.0, v56
	v_add_f32_e32 v57, 1.0, v57
	v_add_f32_e32 v58, 1.0, v58
	v_add_f32_e32 v59, 1.0, v59
	v_add_f32_e32 v72, 1.0, v60
	v_add_f32_e32 v73, 1.0, v61
	v_add_f32_e32 v74, 1.0, v62
	v_add_f32_e32 v75, 1.0, v63
	v_rcp_f32_e32 v60, v56
	v_rcp_f32_e32 v56, v57
	v_rcp_f32_e32 v61, v58
	v_rcp_f32_e32 v57, v59
	v_rcp_f32_e32 v62, v72
	v_rcp_f32_e32 v58, v73
	v_rcp_f32_e32 v63, v74
	v_rcp_f32_e32 v59, v75
.LBB0_785:
	s_and_b64 vcc, exec, s[6:7]
	v_cvt_pk_bf16_f32 v60, v60, v61
	v_cvt_pk_bf16_f32 v61, v62, v63
	v_cvt_pk_bf16_f32 v62, v56, v57
	v_cvt_pk_bf16_f32 v63, v58, v59
	s_nop 0
	ds_write_b128 v153, v[60:63]
	s_cbranch_vccnz .LBB0_787
	v_fma_f32 v56, v52, s99, v184
	v_fma_f32 v60, v48, s99, v188
	v_fma_f32 v57, v53, s99, v185
	v_fma_f32 v61, v49, s99, v189
	v_fma_f32 v58, v54, s99, v186
	v_fma_f32 v62, v50, s99, v190
	v_fma_f32 v59, v55, s99, v187
	v_fma_f32 v63, v51, s99, v191
	v_exp_f32_e32 v48, v56
	v_exp_f32_e32 v49, v60
	v_exp_f32_e32 v50, v57
	v_exp_f32_e32 v51, v61
	v_exp_f32_e32 v52, v58
	v_exp_f32_e32 v53, v62
	v_exp_f32_e32 v54, v59
	v_exp_f32_e32 v55, v63
	v_add_f32_e32 v48, 1.0, v48
	v_add_f32_e32 v49, 1.0, v49
	v_add_f32_e32 v50, 1.0, v50
	v_add_f32_e32 v51, 1.0, v51
	v_add_f32_e32 v56, 1.0, v52
	v_add_f32_e32 v57, 1.0, v53
	v_add_f32_e32 v58, 1.0, v54
	v_add_f32_e32 v59, 1.0, v55
	v_rcp_f32_e32 v52, v48
	v_rcp_f32_e32 v48, v49
	v_rcp_f32_e32 v53, v50
	v_rcp_f32_e32 v49, v51
	v_rcp_f32_e32 v54, v56
	v_rcp_f32_e32 v50, v57
	v_rcp_f32_e32 v55, v58
	v_rcp_f32_e32 v51, v59
.LBB0_787:
	v_add_co_u32_e32 v56, vcc, 0xa8000, v104
	v_cvt_pk_bf16_f32 v52, v52, v53
	v_cvt_pk_bf16_f32 v53, v54, v55
	v_cvt_pk_bf16_f32 v54, v48, v49
	v_cvt_pk_bf16_f32 v55, v50, v51
	s_nop 1
	v_addc_co_u32_e32 v57, vcc, 0, v105, vcc
	ds_write_b128 v153, v[52:55] offset:64
	ds_read_b128 v[52:55], v154
	ds_read_b128 v[48:51], v154 offset:1152
	s_waitcnt lgkmcnt(4)
	global_store_dwordx4 v[56:57], v[68:71], off nt
	v_add_co_u32_e32 v56, vcc, 0xc4000, v104
	s_nop 1
	v_addc_co_u32_e32 v57, vcc, 0, v105, vcc
	s_and_b64 vcc, exec, s[6:7]
	global_store_dwordx4 v[56:57], v[64:67], off nt
	s_cbranch_vccnz .LBB0_789
	v_fma_f32 v56, v44, s99, v176
	v_fma_f32 v60, v40, s99, v180
	v_fma_f32 v57, v45, s99, v177
	v_fma_f32 v61, v41, s99, v181
	v_fma_f32 v58, v46, s99, v178
	v_fma_f32 v62, v42, s99, v182
	v_fma_f32 v59, v47, s99, v179
	v_fma_f32 v63, v43, s99, v183
	v_exp_f32_e32 v40, v56
	v_exp_f32_e32 v41, v60
	v_exp_f32_e32 v42, v57
	v_exp_f32_e32 v43, v61
	v_exp_f32_e32 v44, v58
	v_exp_f32_e32 v45, v62
	v_exp_f32_e32 v46, v59
	v_exp_f32_e32 v47, v63
	v_add_f32_e32 v40, 1.0, v40
	v_add_f32_e32 v41, 1.0, v41
	v_add_f32_e32 v42, 1.0, v42
	v_add_f32_e32 v43, 1.0, v43
	v_add_f32_e32 v56, 1.0, v44
	v_add_f32_e32 v57, 1.0, v45
	v_add_f32_e32 v58, 1.0, v46
	v_add_f32_e32 v59, 1.0, v47
	v_rcp_f32_e32 v44, v40
	v_rcp_f32_e32 v40, v41
	v_rcp_f32_e32 v45, v42
	v_rcp_f32_e32 v41, v43
	v_rcp_f32_e32 v46, v56
	v_rcp_f32_e32 v42, v57
	v_rcp_f32_e32 v47, v58
	v_rcp_f32_e32 v43, v59
.LBB0_789:
	s_and_b64 vcc, exec, s[6:7]
	v_cvt_pk_bf16_f32 v44, v44, v45
	v_cvt_pk_bf16_f32 v45, v46, v47
	v_cvt_pk_bf16_f32 v46, v40, v41
	v_cvt_pk_bf16_f32 v47, v42, v43
	s_nop 0
	ds_write_b128 v153, v[44:47]
	s_cbranch_vccnz .LBB0_791
	v_fma_f32 v40, v36, s99, v184
	v_fma_f32 v44, v32, s99, v188
	v_fma_f32 v41, v37, s99, v185
	v_fma_f32 v45, v33, s99, v189
	v_fma_f32 v42, v38, s99, v186
	v_fma_f32 v46, v34, s99, v190
	v_fma_f32 v43, v39, s99, v187
	v_fma_f32 v47, v35, s99, v191
	v_exp_f32_e32 v32, v40
	v_exp_f32_e32 v33, v44
	v_exp_f32_e32 v34, v41
	v_exp_f32_e32 v35, v45
	v_exp_f32_e32 v36, v42
	v_exp_f32_e32 v37, v46
	v_exp_f32_e32 v38, v43
	v_exp_f32_e32 v39, v47
	v_add_f32_e32 v32, 1.0, v32
	v_add_f32_e32 v33, 1.0, v33
	v_add_f32_e32 v34, 1.0, v34
	v_add_f32_e32 v35, 1.0, v35
	v_add_f32_e32 v40, 1.0, v36
	v_add_f32_e32 v41, 1.0, v37
	v_add_f32_e32 v42, 1.0, v38
	v_add_f32_e32 v43, 1.0, v39
	v_rcp_f32_e32 v36, v32
	v_rcp_f32_e32 v32, v33
	v_rcp_f32_e32 v37, v34
	v_rcp_f32_e32 v33, v35
	v_rcp_f32_e32 v38, v40
	v_rcp_f32_e32 v34, v41
	v_rcp_f32_e32 v39, v42
	v_rcp_f32_e32 v35, v43
; #define GAS1 __attribute__((address_space(1)))
;     __device__ __forceinline__ void operator()(const f32x4 (&acc)[2][2][4][2], const Unit& u, int wr, int wc, int fr, int fq) const {
;     ...
;                 f32x4 v0 = acc[ai][bj][m][0], v1 = acc[ai][bj][m][1];
;                 if (MODE == 1) {
;                     if (special) {
;                         const f32x4 b0 = *(const GAS1 f32x4*)(bias + col) * -1.4426950408889634f, b1 = *(const GAS1 f32x4*)(bias + col + 4) * -1.4426950408889634f;
; #pragma unroll
;                         for (int j = 0; j < 4; ++j) { v0[j] = __builtin_amdgcn_rcpf(1.0f + __builtin_amdgcn_exp2f(__builtin_fmaf(v0[j], -1.4426950408889634f, b0[j])));
;                                                       v1[j] = __builtin_amdgcn_rcpf(1.0f + __builtin_amdgcn_exp2f(__builtin_fmaf(v1[j], -1.4426950408889634f, b1[j]))); }
;                     }
;                 }
;                 if (MODE == 2) {
;                     if (special) {
;                         const int fi = ((col & 63) >> 3) * 4;
;                         const f32x4 c = *(const GAS1 f32x4*)(cosT + (size_t)row * 32 + fi), s_ = *(const GAS1 f32x4*)(sinT + (size_t)row * 32 + fi);
;                         const f32x4 o1 = v0 * c - v1 * s_, o2 = v1 * c + v0 * s_; v0 = o1; v1 = o2;
;                     }
;                 }
;                 if (MODE == 3 || MODE == 4) {
;                     const u32x4 gw = *(const GAS1 u32x4*)(G + (size_t)row * ldg + col);
;                     const f32x4 g0 = {bf_lo(gw.x), bf_hi(gw.x), bf_lo(gw.y), bf_hi(gw.y)}, g1 = {bf_lo(gw.z), bf_hi(gw.z), bf_lo(gw.w), bf_hi(gw.w)};
;                     v0 = v0 * g0; v1 = v1 * g1;
;                     if (MODE == 4) {
;                         const u32x4 ow = *(const GAS1 u32x4*)((const bf16_t*)O + (size_t)row * ldc + col);
;                         const f32x4 o0 = {bf_lo(ow.x), bf_hi(ow.x), bf_lo(ow.y), bf_hi(ow.y)}, o1 = {bf_lo(ow.z), bf_hi(ow.z), bf_lo(ow.w), bf_hi(ow.w)};
;                         v0 += o0; v1 += o1;
;                     }
;                 }
;                 u32x4 w; w.x = cvt_pk_bf16(v0[0], v0[1]); w.y = cvt_pk_bf16(v0[2], v0[3]); w.z = cvt_pk_bf16(v1[0], v1[1]); w.w = cvt_pk_bf16(v1[2], v1[3]);
;                 if (bj == 0) asm volatile("ds_write_b128 %0, %1" :: "v"(wa), "v"(w)); else asm volatile("ds_write_b128 %0, %1 offset:64" :: "v"(wa), "v"(w));
;             }
.LBB0_791:
	v_add_co_u32_e32 v40, vcc, 0x1c0000, v104
	v_cvt_pk_bf16_f32 v36, v36, v37
	v_cvt_pk_bf16_f32 v37, v38, v39
	v_cvt_pk_bf16_f32 v38, v32, v33
	v_cvt_pk_bf16_f32 v39, v34, v35
	s_nop 1
	v_addc_co_u32_e32 v41, vcc, 0, v105, vcc
	ds_write_b128 v153, v[36:39] offset:64
	ds_read_b128 v[36:39], v154
	ds_read_b128 v[32:35], v154 offset:1152
	s_waitcnt lgkmcnt(4)
	global_store_dwordx4 v[40:41], v[52:55], off nt
	v_add_co_u32_e32 v40, vcc, 0x1dc000, v104
	s_nop 1
	v_addc_co_u32_e32 v41, vcc, 0, v105, vcc
	s_and_b64 vcc, exec, s[6:7]
	global_store_dwordx4 v[40:41], v[48:51], off nt
	s_cbranch_vccnz .LBB0_793
	v_fma_f32 v40, v28, s99, v176
	v_fma_f32 v44, v24, s99, v180
	v_fma_f32 v41, v29, s99, v177
	v_fma_f32 v45, v25, s99, v181
	v_fma_f32 v42, v30, s99, v178
	v_fma_f32 v46, v26, s99, v182
	v_fma_f32 v43, v31, s99, v179
	v_fma_f32 v47, v27, s99, v183
	v_exp_f32_e32 v24, v40
	v_exp_f32_e32 v25, v44
	v_exp_f32_e32 v26, v41
	v_exp_f32_e32 v27, v45
	v_exp_f32_e32 v28, v42
	v_exp_f32_e32 v29, v46
	v_exp_f32_e32 v30, v43
	v_exp_f32_e32 v31, v47
	v_add_f32_e32 v24, 1.0, v24
	v_add_f32_e32 v25, 1.0, v25
	v_add_f32_e32 v26, 1.0, v26
	v_add_f32_e32 v27, 1.0, v27
	v_add_f32_e32 v40, 1.0, v28
	v_add_f32_e32 v41, 1.0, v29
	v_add_f32_e32 v42, 1.0, v30
	v_add_f32_e32 v43, 1.0, v31
	v_rcp_f32_e32 v28, v24
	v_rcp_f32_e32 v24, v25
	v_rcp_f32_e32 v29, v26
	v_rcp_f32_e32 v25, v27
	v_rcp_f32_e32 v30, v40
	v_rcp_f32_e32 v26, v41
	v_rcp_f32_e32 v31, v42
	v_rcp_f32_e32 v27, v43
.LBB0_793:
	s_and_b64 vcc, exec, s[6:7]
	v_cvt_pk_bf16_f32 v28, v28, v29
	v_cvt_pk_bf16_f32 v29, v30, v31
	v_cvt_pk_bf16_f32 v30, v24, v25
	v_cvt_pk_bf16_f32 v31, v26, v27
	s_nop 0
	ds_write_b128 v153, v[28:31]
	s_cbranch_vccnz .LBB0_795
	v_fma_f32 v24, v20, s99, v184
	v_fma_f32 v28, v16, s99, v188
	v_fma_f32 v25, v21, s99, v185
	v_fma_f32 v29, v17, s99, v189
	v_fma_f32 v26, v22, s99, v186
	v_fma_f32 v30, v18, s99, v190
	v_fma_f32 v27, v23, s99, v187
	v_fma_f32 v31, v19, s99, v191
	v_exp_f32_e32 v16, v24
	v_exp_f32_e32 v17, v28
	v_exp_f32_e32 v18, v25
	v_exp_f32_e32 v19, v29
	v_exp_f32_e32 v20, v26
	v_exp_f32_e32 v21, v30
	v_exp_f32_e32 v22, v27
	v_exp_f32_e32 v23, v31
	v_add_f32_e32 v16, 1.0, v16
	v_add_f32_e32 v17, 1.0, v17
	v_add_f32_e32 v18, 1.0, v18
	v_add_f32_e32 v19, 1.0, v19
	v_add_f32_e32 v24, 1.0, v20
	v_add_f32_e32 v25, 1.0, v21
	v_add_f32_e32 v26, 1.0, v22
	v_add_f32_e32 v27, 1.0, v23
	v_rcp_f32_e32 v20, v16
	v_rcp_f32_e32 v16, v17
	v_rcp_f32_e32 v21, v18
	v_rcp_f32_e32 v17, v19
	v_rcp_f32_e32 v22, v24
	v_rcp_f32_e32 v18, v25
	v_rcp_f32_e32 v23, v26
	v_rcp_f32_e32 v19, v27
.LBB0_795:
	v_add_co_u32_e32 v24, vcc, 0x1f8000, v104
	v_cvt_pk_bf16_f32 v20, v20, v21
	v_cvt_pk_bf16_f32 v21, v22, v23
	v_cvt_pk_bf16_f32 v22, v16, v17
	v_cvt_pk_bf16_f32 v23, v18, v19
	s_nop 1
	v_addc_co_u32_e32 v25, vcc, 0, v105, vcc
	ds_write_b128 v153, v[20:23] offset:64
	ds_read_b128 v[20:23], v154
	ds_read_b128 v[16:19], v154 offset:1152
	s_waitcnt lgkmcnt(4)
	global_store_dwordx4 v[24:25], v[36:39], off nt
	v_add_co_u32_e32 v24, vcc, 0x214000, v104
	s_nop 1
	v_addc_co_u32_e32 v25, vcc, 0, v105, vcc
	s_and_b64 vcc, exec, s[6:7]
	global_store_dwordx4 v[24:25], v[32:35], off nt
	s_cbranch_vccnz .LBB0_797
	v_fma_f32 v24, v12, s99, v176
	v_fma_f32 v28, v8, s99, v180
	v_fma_f32 v25, v13, s99, v177
	v_fma_f32 v29, v9, s99, v181
	v_fma_f32 v26, v14, s99, v178
	v_fma_f32 v30, v10, s99, v182
	v_fma_f32 v27, v15, s99, v179
	v_fma_f32 v31, v11, s99, v183
	v_exp_f32_e32 v8, v24
	v_exp_f32_e32 v9, v28
	v_exp_f32_e32 v10, v25
	v_exp_f32_e32 v11, v29
	v_exp_f32_e32 v12, v26
	v_exp_f32_e32 v13, v30
	v_exp_f32_e32 v14, v27
	v_exp_f32_e32 v15, v31
	v_add_f32_e32 v8, 1.0, v8
	v_add_f32_e32 v9, 1.0, v9
	v_add_f32_e32 v10, 1.0, v10
	v_add_f32_e32 v11, 1.0, v11
	v_add_f32_e32 v24, 1.0, v12
	v_add_f32_e32 v25, 1.0, v13
	v_add_f32_e32 v26, 1.0, v14
	v_add_f32_e32 v27, 1.0, v15
	v_rcp_f32_e32 v12, v8
	v_rcp_f32_e32 v8, v9
	v_rcp_f32_e32 v13, v10
	v_rcp_f32_e32 v9, v11
	v_rcp_f32_e32 v14, v24
	v_rcp_f32_e32 v10, v25
	v_rcp_f32_e32 v15, v26
	v_rcp_f32_e32 v11, v27
.LBB0_797:
	s_and_b64 vcc, exec, s[6:7]
	v_cvt_pk_bf16_f32 v12, v12, v13
	v_cvt_pk_bf16_f32 v13, v14, v15
	v_cvt_pk_bf16_f32 v14, v8, v9
	v_cvt_pk_bf16_f32 v15, v10, v11
	s_nop 0
	ds_write_b128 v153, v[12:15]
	s_cbranch_vccnz .LBB0_799
	v_fma_f32 v8, v4, s99, v184
	v_fma_f32 v12, v0, s99, v188
	v_fma_f32 v9, v5, s99, v185
	v_fma_f32 v13, v1, s99, v189
	v_fma_f32 v10, v6, s99, v186
	v_fma_f32 v14, v2, s99, v190
	v_fma_f32 v11, v7, s99, v187
	v_fma_f32 v15, v3, s99, v191
	v_exp_f32_e32 v0, v8
	v_exp_f32_e32 v1, v12
	v_exp_f32_e32 v2, v9
	v_exp_f32_e32 v3, v13
	v_exp_f32_e32 v4, v10
	v_exp_f32_e32 v5, v14
	v_exp_f32_e32 v6, v11
	v_exp_f32_e32 v7, v15
	v_add_f32_e32 v0, 1.0, v0
	v_add_f32_e32 v1, 1.0, v1
	v_add_f32_e32 v2, 1.0, v2
	v_add_f32_e32 v3, 1.0, v3
	v_add_f32_e32 v8, 1.0, v4
	v_add_f32_e32 v9, 1.0, v5
	v_add_f32_e32 v10, 1.0, v6
	v_add_f32_e32 v11, 1.0, v7
	v_rcp_f32_e32 v4, v0
	v_rcp_f32_e32 v0, v1
	v_rcp_f32_e32 v5, v2
	v_rcp_f32_e32 v1, v3
	v_rcp_f32_e32 v6, v8
	v_rcp_f32_e32 v2, v9
	v_rcp_f32_e32 v7, v10
	v_rcp_f32_e32 v3, v11
